# v30 plus rglru gate segment in packed f32 math with gate MFMAs ordered so the first channel block starts under the second block's MFMAs
# speedup vs baseline: 1.0012x; 1.0012x over previous
; #define LAS __attribute__((address_space(3)))
; __device__ __forceinline__ float fsigmoid(float x) { return __builtin_amdgcn_rcpf(1.0f + __builtin_amdgcn_exp2f(-1.4426950408889634f * x)); }
; __device__ __forceinline__ void rglru_unit(LAS unsigned char* lds, int unit, const bf16* PBp, bf16* MGp, float* SSQRp, const float* cw, const float* cbias, const float* wa, const float* ba, const float* wx, const float* bxp, const float* lam) {
;     ...
;         {
;             typedef float f32x4m __attribute__((ext_vector_type(4)));
;             const rg_bf16x8 a0 = *(const LAS rg_bf16x8*)(XRB + (wave * 16 + fr) * 72 + 8 * fq), a1 = *(const LAS rg_bf16x8*)(XRB + (wave * 16 + fr) * 72 + 32 + 8 * fq);
;             f32x4m d[4];
; #pragma unroll
;             for (int nb = 0; nb < 4; ++nb) { d[nb] = (f32x4m){0.f, 0.f, 0.f, 0.f};
;                 d[nb] = __builtin_amdgcn_mfma_f32_16x16x32_bf16(a0, wb[nb][0], d[nb], 0, 0, 0); d[nb] = __builtin_amdgcn_mfma_f32_16x16x32_bf16(a1, wb[nb][1], d[nb], 0, 0, 0); }
; #pragma unroll
;             for (int cb = 0; cb < 2; ++cb)
; #pragma unroll
;                 for (int e = 0; e < 4; ++e) {
;                     const int tok = wave * 16 + 4 * fq + e, cl = 16 * cb + fr;
;                     const float r = fsigmoid(d[cb][e] + gba[cb]), ig = fsigmoid(d[2 + cb][e] + gbx[cb]);
;                     const float a = __builtin_amdgcn_exp2f(r * gsp[cb]);
;                     const float om = fmaxf(1.0f - a * a, 0.0f);
;                     AL[tok * 32 + cl] = a; UL[tok * 32 + cl] = __builtin_amdgcn_sqrtf(om) * (ig * XRF[tok * 32 + cl]);
;                 }
;         }
.LBB0_452:
	s_waitcnt lgkmcnt(0)
	s_barrier
	ds_read_b128 v[72:75], v134
	ds_read_b128 v[76:79], v134 offset:64
	v_add_u32_e32 v1, 0x4800, v138
	ds_read2_b32 v[92:93], v1 offset1:32
	ds_read2_b32 v[94:95], v1 offset0:64 offset1:96
	ds_read2_b32 v[96:97], v1 offset0:16 offset1:48
	ds_read2_b32 v[98:99], v1 offset0:80 offset1:112
	v_mov_b32_e32 v2, 0xbfb8aa3b
	v_mov_b32_e32 v120, 1.0
	v_mov_b32_e32 v112, v123
	v_mov_b32_e32 v114, v125
	v_mov_b32_e32 v116, v127
	s_waitcnt lgkmcnt(4)
	v_mfma_f32_16x16x32_bf16 v[80:83], v[72:75], v[20:23], 0
	v_mfma_f32_16x16x32_bf16 v[84:87], v[72:75], v[52:55], 0
	v_mfma_f32_16x16x32_bf16 v[80:83], v[76:79], v[32:35], v[80:83]
	v_mfma_f32_16x16x32_bf16 v[84:87], v[76:79], v[56:59], v[84:87]
	v_mfma_f32_16x16x32_bf16 v[88:91], v[72:75], v[36:39], 0
	v_mfma_f32_16x16x32_bf16 v[108:111], v[72:75], v[60:63], 0
	v_mfma_f32_16x16x32_bf16 v[88:91], v[76:79], v[48:51], v[88:91]
	v_mfma_f32_16x16x32_bf16 v[108:111], v[76:79], v[64:67], v[108:111]
	v_add_u32_e32 v3, 0x8800, v138
	v_add_u32_e32 v121, 0xc800, v138
	s_nop 3
	s_waitcnt lgkmcnt(0)
	v_pk_add_f32 v[80:81], v[80:81], v[122:123] op_sel_hi:[1,0]
	v_pk_add_f32 v[84:85], v[84:85], v[112:113] op_sel_hi:[1,0]
	v_pk_mul_f32 v[80:81], v[80:81], v[2:3] op_sel_hi:[1,0]
	v_pk_mul_f32 v[84:85], v[84:85], v[2:3] op_sel_hi:[1,0]
	v_exp_f32_e32 v80, v80
	v_exp_f32_e32 v81, v81
	v_exp_f32_e32 v84, v84
	v_exp_f32_e32 v85, v85
	v_pk_add_f32 v[80:81], v[80:81], v[120:121] op_sel_hi:[1,0]
	v_pk_add_f32 v[84:85], v[84:85], v[120:121] op_sel_hi:[1,0]
	v_rcp_f32_e32 v80, v80
	v_rcp_f32_e32 v81, v81
	v_rcp_f32_e32 v84, v84
	v_rcp_f32_e32 v85, v85
	v_pk_mul_f32 v[118:119], v[80:81], v[128:129] op_sel_hi:[1,0]
	v_pk_mul_f32 v[78:79], v[92:93], v[84:85]
	v_exp_f32_e32 v118, v118
	v_exp_f32_e32 v119, v119
	s_nop 0
	v_fma_f32 v76, -v118, v118, 1.0
	v_fma_f32 v77, -v119, v119, 1.0
	v_max_f32_e32 v76, 0, v76
	v_max_f32_e32 v77, 0, v77
	v_sqrt_f32_e32 v76, v76
	v_sqrt_f32_e32 v77, v77
	ds_write2_b32 v3, v118, v119 offset0:0 offset1:32
	v_pk_mul_f32 v[78:79], v[78:79], v[76:77]
	ds_write2_b32 v121, v78, v79 offset0:0 offset1:32
	v_pk_add_f32 v[82:83], v[82:83], v[122:123] op_sel_hi:[1,0]
	v_pk_add_f32 v[86:87], v[86:87], v[112:113] op_sel_hi:[1,0]
	v_pk_mul_f32 v[82:83], v[82:83], v[2:3] op_sel_hi:[1,0]
	v_pk_mul_f32 v[86:87], v[86:87], v[2:3] op_sel_hi:[1,0]
	v_exp_f32_e32 v82, v82
	v_exp_f32_e32 v83, v83
	v_exp_f32_e32 v86, v86
	v_exp_f32_e32 v87, v87
	v_pk_add_f32 v[82:83], v[82:83], v[120:121] op_sel_hi:[1,0]
	v_pk_add_f32 v[86:87], v[86:87], v[120:121] op_sel_hi:[1,0]
	v_rcp_f32_e32 v82, v82
	v_rcp_f32_e32 v83, v83
	v_rcp_f32_e32 v86, v86
	v_rcp_f32_e32 v87, v87
	v_pk_mul_f32 v[118:119], v[82:83], v[128:129] op_sel_hi:[1,0]
	v_pk_mul_f32 v[78:79], v[94:95], v[86:87]
	v_exp_f32_e32 v118, v118
	v_exp_f32_e32 v119, v119
	s_nop 0
	v_fma_f32 v76, -v118, v118, 1.0
	v_fma_f32 v77, -v119, v119, 1.0
	v_max_f32_e32 v76, 0, v76
	v_max_f32_e32 v77, 0, v77
	v_sqrt_f32_e32 v76, v76
	v_sqrt_f32_e32 v77, v77
	ds_write2_b32 v3, v118, v119 offset0:64 offset1:96
	v_pk_mul_f32 v[78:79], v[78:79], v[76:77]
	ds_write2_b32 v121, v78, v79 offset0:64 offset1:96
	v_pk_add_f32 v[88:89], v[88:89], v[124:125] op_sel_hi:[1,0]
	v_pk_add_f32 v[108:109], v[108:109], v[114:115] op_sel_hi:[1,0]
	v_pk_mul_f32 v[88:89], v[88:89], v[2:3] op_sel_hi:[1,0]
	v_pk_mul_f32 v[108:109], v[108:109], v[2:3] op_sel_hi:[1,0]
	v_exp_f32_e32 v88, v88
	v_exp_f32_e32 v89, v89
	v_exp_f32_e32 v108, v108
	v_exp_f32_e32 v109, v109
	v_pk_add_f32 v[88:89], v[88:89], v[120:121] op_sel_hi:[1,0]
	v_pk_add_f32 v[108:109], v[108:109], v[120:121] op_sel_hi:[1,0]
	v_rcp_f32_e32 v88, v88
	v_rcp_f32_e32 v89, v89
	v_rcp_f32_e32 v108, v108
	v_rcp_f32_e32 v109, v109
	v_pk_mul_f32 v[118:119], v[88:89], v[116:117] op_sel_hi:[1,0]
	v_pk_mul_f32 v[78:79], v[96:97], v[108:109]
	v_exp_f32_e32 v118, v118
	v_exp_f32_e32 v119, v119
	s_nop 0
	v_fma_f32 v76, -v118, v118, 1.0
	v_fma_f32 v77, -v119, v119, 1.0
	v_max_f32_e32 v76, 0, v76
	v_max_f32_e32 v77, 0, v77
	v_sqrt_f32_e32 v76, v76
	v_sqrt_f32_e32 v77, v77
	ds_write2_b32 v3, v118, v119 offset0:16 offset1:48
	v_pk_mul_f32 v[78:79], v[78:79], v[76:77]
	ds_write2_b32 v121, v78, v79 offset0:16 offset1:48
	v_pk_add_f32 v[90:91], v[90:91], v[124:125] op_sel_hi:[1,0]
	v_pk_add_f32 v[110:111], v[110:111], v[114:115] op_sel_hi:[1,0]
	v_pk_mul_f32 v[90:91], v[90:91], v[2:3] op_sel_hi:[1,0]
	v_pk_mul_f32 v[110:111], v[110:111], v[2:3] op_sel_hi:[1,0]
	v_exp_f32_e32 v90, v90
	v_exp_f32_e32 v91, v91
	v_exp_f32_e32 v110, v110
	v_exp_f32_e32 v111, v111
	v_pk_add_f32 v[90:91], v[90:91], v[120:121] op_sel_hi:[1,0]
	v_pk_add_f32 v[110:111], v[110:111], v[120:121] op_sel_hi:[1,0]
	v_rcp_f32_e32 v90, v90
	v_rcp_f32_e32 v91, v91
	v_rcp_f32_e32 v110, v110
	v_rcp_f32_e32 v111, v111
	v_pk_mul_f32 v[118:119], v[90:91], v[116:117] op_sel_hi:[1,0]
	v_pk_mul_f32 v[78:79], v[98:99], v[110:111]
	v_exp_f32_e32 v118, v118
	v_exp_f32_e32 v119, v119
	s_nop 0
	v_fma_f32 v76, -v118, v118, 1.0
	v_fma_f32 v77, -v119, v119, 1.0
	v_max_f32_e32 v76, 0, v76
	v_max_f32_e32 v77, 0, v77
	v_sqrt_f32_e32 v76, v76
	v_sqrt_f32_e32 v77, v77
	ds_write2_b32 v3, v118, v119 offset0:80 offset1:112
	v_pk_mul_f32 v[78:79], v[78:79], v[76:77]
	ds_write2_b32 v121, v78, v79 offset0:80 offset1:112
	v_add_u32_e32 v1, 0x8800, v140
	s_waitcnt lgkmcnt(0)
	s_barrier
; #define LAS __attribute__((address_space(3)))
; __device__ __forceinline__ void rglru_unit(LAS unsigned char* lds, int unit, const bf16* PBp, bf16* MGp, float* SSQRp, const float* cw, const float* cbias, const float* wa, const float* ba, const float* wx, const float* bxp, const float* lam) {
;     ...
;         float av[8], uv[8];
; #pragma unroll
;         for (int k = 0; k < 8; ++k) { av[k] = AL[(ss * 8 + k) * 32 + sc]; uv[k] = UL[(ss * 8 + k) * 32 + sc]; }
;         { float h = 0.f, p = 1.f;
; #pragma unroll
;           for (int k = 0; k < 8; ++k) { h = av[k] * h + uv[k]; p *= av[k]; }
;           PE[(ss * 32 + sc) * 2] = p; PE[(ss * 32 + sc) * 2 + 1] = h; }
;         __syncthreads();
;         float h = HIN[sc];
;         { typedef float f32x2v __attribute__((ext_vector_type(2))); f32x2v pe[15];
; #pragma unroll
;           for (int s2 = 0; s2 < 15; ++s2) pe[s2] = *(const LAS f32x2v*)(PE + (s2 * 32 + sc) * 2);
; #pragma unroll
;           for (int s2 = 0; s2 < 15; ++s2) h = (s2 < ss) ? fmaf(pe[s2].x, h, pe[s2].y) : h; }
	ds_read2_b32 v[120:121], v1 offset1:32
	v_add_u32_e32 v2, 0xc800, v140
	ds_read2_b32 v[118:119], v2 offset1:32
	ds_read2_b32 v[116:117], v1 offset0:64 offset1:96
	ds_read2_b32 v[114:115], v2 offset0:64 offset1:96
	ds_read2_b32 v[112:113], v1 offset0:128 offset1:160
	ds_read2_b32 v[110:111], v2 offset0:128 offset1:160
	ds_read2_b32 v[108:109], v1 offset0:192 offset1:224
	ds_read2_b32 v[2:3], v2 offset0:192 offset1:224
	s_waitcnt lgkmcnt(5)
	v_mov_b32_e32 v74, v116
	s_waitcnt lgkmcnt(3)
	v_mov_b32_e32 v75, v113
	v_fma_f32 v1, 0, v120, v118
	v_fma_f32 v1, v1, v121, v119
	v_fma_f32 v1, v1, v116, v114
	v_fma_f32 v1, v1, v117, v115
	v_mul_f32_e32 v72, v120, v121
	s_waitcnt lgkmcnt(2)
	v_fma_f32 v73, v1, v112, v110
	v_mov_b32_e32 v76, v117
	v_mov_b32_e32 v77, v111
	v_mul_f32_e32 v1, v72, v116
	v_pk_fma_f32 v[72:73], v[72:73], v[74:75], v[76:77]
	v_mul_f32_e32 v78, v1, v117
	v_mov_b32_e32 v79, v73
	v_mov_b32_e32 v72, v112
	s_waitcnt lgkmcnt(1)
	v_mov_b32_e32 v73, v108
	v_pk_mul_f32 v[74:75], v[78:79], v[72:73]
	v_mov_b32_e32 v76, v113
	v_mov_b32_e32 v80, v113
	s_waitcnt lgkmcnt(0)
	v_mov_b32_e32 v81, v2
	v_pk_mul_f32 v[74:75], v[74:75], v[76:77]
	v_pk_fma_f32 v[72:73], v[78:79], v[72:73], v[80:81]
	v_mov_b32_e32 v76, v109
	v_mov_b32_e32 v72, v74
	v_pk_mul_f32 v[74:75], v[74:75], v[108:109]
	v_mov_b32_e32 v78, v109
	v_mov_b32_e32 v79, v3
	v_pk_mul_f32 v[74:75], v[74:75], v[76:77]
	v_pk_fma_f32 v[72:73], v[72:73], v[108:109], v[78:79]
	s_nop 0
	v_mov_b32_e32 v75, v73
	v_add_u32_e32 v72, s89, v136
	ds_write_b64 v143, v[74:75]
	s_waitcnt lgkmcnt(0)
	s_barrier
	ds_read_b32 v1, v135
	ds_read2_b64 v[96:99], v72 offset0:32 offset1:64
	ds_read2_b64 v[92:95], v72 offset0:96 offset1:128
	ds_read2_b64 v[88:91], v72 offset0:160 offset1:192
	v_add_u32_e32 v73, 0x400, v72
	v_add_u32_e32 v72, 0x800, v72
	ds_read2_b64 v[84:87], v73 offset0:96 offset1:128
	ds_read2_b64 v[80:83], v72 offset0:32 offset1:64
	ds_read2_b64 v[76:79], v72 offset0:96 offset1:128
	ds_read2_b64 v[72:75], v72 offset0:160 offset1:192
	s_and_saveexec_b64 s[2:3], s[8:9]
	s_cbranch_execz .LBB0_454
	v_add_u32_e32 v154, 0, v136
	v_add_u32_e32 v154, 0x10800, v154
	ds_read_b64 v[154:155], v154
	s_waitcnt lgkmcnt(0)
	v_fmac_f32_e32 v155, v154, v1
	v_mov_b32_e32 v1, v155
